# scan: the two all-zero causal-mask attention fragments are neither written to LDS by the loaders nor read/multiplied by the compute waves (LDS-bandwidth-bound loop: -48 of ~1424 LDS cycles per chunk)
# baseline (speedup 1.0000x reference)
.LBB0_1550:
	s_and_b64 vcc, exec, s[0:1]
	s_cbranch_vccz .LBB0_1544
	v_readlane_b32 s76, v253, 32
	s_mul_i32 s0, s4, 0x600
	s_add_i32 s76, s76, -2
	s_add_i32 s0, s0, s5
	s_and_b32 s77, s12, 3
	s_lshl_b32 s1, s0, 14
	s_lshl_b32 s8, s0, 13
	s_lshl_b32 s9, s76, 10
	s_lshl_b32 s10, s0, 2
	s_add_i32 s11, s9, s1
	s_add_i32 s11, s11, 0x4400000
	s_add_u32 s44, s34, s11
	s_addc_u32 s45, s35, 0
	s_add_i32 s11, s9, s1
	s_add_i32 s11, s11, 0x4401800
	s_add_u32 s46, s34, s11
	s_addc_u32 s47, s35, 0
	s_add_i32 s11, s9, s1
	s_mov_b32 s22, 0x4403000
	s_cmp_lt_u32 s76, 4
	s_cselect_b32 s22, s22, 0x73ff000
	s_add_i32 s11, s11, s22
	s_add_u32 s48, s34, s11
	s_addc_u32 s49, s35, 0
	s_add_i32 s11, s9, s1
	s_add_i32 s11, s11, 0x7400800
	s_add_u32 s50, s34, s11
	s_addc_u32 s51, s35, 0
	s_add_i32 s11, s9, s1
	s_add_i32 s11, s11, 0x7402000
	s_add_u32 s52, s34, s11
	s_addc_u32 s53, s35, 0
	s_add_i32 s11, s9, s1
	s_mov_b32 s22, 0x7403800
	s_cmp_lt_u32 s76, 2
	s_cselect_b32 s22, s22, 0x193ff800
	s_add_i32 s11, s11, s22
	s_add_u32 s54, s34, s11
	s_addc_u32 s55, s35, 0
	s_add_i32 s11, s9, s1
	s_add_i32 s11, s11, 0x19401000
	s_add_u32 s56, s34, s11
	s_addc_u32 s57, s35, 0
	s_add_i32 s11, s9, s1
	s_add_i32 s11, s11, 0x19402800
	s_add_u32 s58, s34, s11
	s_addc_u32 s59, s35, 0
	s_add_i32 s11, s9, s8
	s_add_i32 s11, s11, 0xa400000
	s_add_u32 s60, s34, s11
	s_addc_u32 s61, s35, 0
	s_lshl_b32 s23, s77, 12
	s_add_i32 s22, s9, s8
	s_add_i32 s22, s22, 0xa401800
	s_add_i32 s11, s9, s1
	s_add_i32 s11, s11, s23
	s_add_i32 s11, s11, 0x1c3ff800
	s_mov_b32 s83, 0xc000
	s_cmp_lt_u32 s76, 2
	s_cselect_b32 s11, s22, s11
	s_cselect_b32 s83, s83, 0x18000
	s_add_u32 s62, s34, s11
	s_addc_u32 s63, s35, 0
	s_add_i32 s11, s10, 0x3f2a000
	s_add_u32 s72, s34, s11
	s_addc_u32 s73, s35, 0
	s_add_i32 s11, s10, 0x4000
	s_add_u32 s74, s34, s11
	s_addc_u32 s75, s35, 0
	s_and_b32 s84, s76, 5
	s_cmp_eq_u32 s84, 1
	s_cselect_b32 s84, 1, 0
	s_mov_b32 s80, 0
	v_mov_b32_e32 v132, 0x20000
	s_mov_b32 s82, 0
	s_cmp_lt_i32 s82, s80
	s_cbranch_scc1 .Lg2l_rdy_0
	s_add_i32 s0, s82, 16
	s_min_i32 s0, s0, 0x100

.Lg2l_rdy_0:
	global_load_dwordx4 v[0:3], v120, s[44:45]
	global_load_dwordx4 v[4:7], v120, s[46:47]
	global_load_dwordx4 v[8:11], v120, s[48:49]
	global_load_dwordx4 v[12:15], v120, s[50:51]
	global_load_dwordx4 v[16:19], v120, s[52:53]
	global_load_dwordx4 v[20:23], v120, s[54:55]
	global_load_dwordx4 v[24:27], v120, s[56:57]
	global_load_dwordx4 v[28:31], v120, s[58:59]
	global_load_dwordx4 v[32:35], v120, s[60:61]
	global_load_dwordx4 v[36:39], v120, s[62:63]
	global_load_dword v127, v121, s[72:73]
	s_add_u32 s44, s44, 0x18000
	s_addc_u32 s45, s45, 0
	s_add_u32 s46, s46, 0x18000
	s_addc_u32 s47, s47, 0
	s_add_u32 s48, s48, 0x18000
	s_addc_u32 s49, s49, 0
	s_add_u32 s50, s50, 0x18000
	s_addc_u32 s51, s51, 0
	s_add_u32 s52, s52, 0x18000
	s_addc_u32 s53, s53, 0
	s_add_u32 s54, s54, 0x18000
	s_addc_u32 s55, s55, 0
	s_add_u32 s56, s56, 0x18000
	s_addc_u32 s57, s57, 0
	s_add_u32 s58, s58, 0x18000
	s_addc_u32 s59, s59, 0
	s_add_u32 s60, s60, 0xc000
	s_addc_u32 s61, s61, 0
	s_add_u32 s62, s62, s83
	s_addc_u32 s63, s63, 0
	s_add_u32 s72, s72, 24
	s_addc_u32 s73, s73, 0
	s_mov_b32 s81, 0
	s_and_b32 s0, s81, 1
	v_lshl_add_u32 v131, s0, 16, v125
	s_waitcnt vmcnt(0)
	ds_write_b128 v131, v[0:3]
	ds_write_b128 v131, v[4:7] offset:6144
	ds_write_b128 v131, v[8:11] offset:12288
	ds_write_b128 v131, v[12:15] offset:18432
	ds_write_b128 v131, v[16:19] offset:24576
	ds_write_b128 v131, v[20:23] offset:30720
	ds_write_b128 v131, v[24:27] offset:36864
	ds_write_b128 v131, v[28:31] offset:43008
	s_cmp_eq_u32 s84, 1
	s_cbranch_scc1 .Lg2l_z_1
	ds_write_b128 v131, v[32:35] offset:49152
.Lg2l_z_1:
	ds_write_b128 v131, v[36:39] offset:55296
	s_and_saveexec_b64 s[8:9], s[6:7]
	s_cbranch_execz .Lg2l_nocd_2
	s_lshl_b32 s0, s0, 2
	v_add_u32_e32 v130, s0, v132
	ds_write_b32 v130, v127

.Lg2l_loop:
	s_cmpk_lt_u32 s81, 0xf0
	s_cbranch_scc0 .Lg2l_tail_3
	s_and_b32 s0, s81, 1
	v_lshl_add_u32 v131, s0, 16, v125
	s_waitcnt vmcnt(22)
	ds_write_b128 v131, v[0:3]
	ds_write_b128 v131, v[4:7] offset:6144
	ds_write_b128 v131, v[8:11] offset:12288
	ds_write_b128 v131, v[12:15] offset:18432
	ds_write_b128 v131, v[16:19] offset:24576
	ds_write_b128 v131, v[20:23] offset:30720
	ds_write_b128 v131, v[24:27] offset:36864
	ds_write_b128 v131, v[28:31] offset:43008
	s_cmp_eq_u32 s84, 1
	s_cbranch_scc1 .Lg2l_z_4
	ds_write_b128 v131, v[32:35] offset:49152

.Lg2l_tail_3:
	s_and_b32 s0, s81, 1
	v_lshl_add_u32 v131, s0, 16, v125
	s_waitcnt vmcnt(0)
	ds_write_b128 v131, v[0:3]
	ds_write_b128 v131, v[4:7] offset:6144
	ds_write_b128 v131, v[8:11] offset:12288
	ds_write_b128 v131, v[12:15] offset:18432
	ds_write_b128 v131, v[16:19] offset:24576
	ds_write_b128 v131, v[20:23] offset:30720
	ds_write_b128 v131, v[24:27] offset:36864
	ds_write_b128 v131, v[28:31] offset:43008
	s_cmp_eq_u32 s84, 1
	s_cbranch_scc1 .Lg2l_z_6
	ds_write_b128 v131, v[32:35] offset:49152

.Lg2l_nold_3:
	s_waitcnt lgkmcnt(0)
	s_barrier
	s_add_i32 s81, s81, 1
	s_cmpk_lt_u32 s81, 0x100
	s_cbranch_scc0 .Lg2l_exit
	s_cmpk_lt_u32 s81, 0xf0
	s_cbranch_scc0 .Lg2l_tail_9
	s_and_b32 s0, s81, 1
	v_lshl_add_u32 v131, s0, 16, v125
	s_waitcnt vmcnt(22)
	ds_write_b128 v131, v[40:43]
	ds_write_b128 v131, v[44:47] offset:6144
	ds_write_b128 v131, v[48:51] offset:12288
	ds_write_b128 v131, v[52:55] offset:18432
	ds_write_b128 v131, v[56:59] offset:24576
	ds_write_b128 v131, v[60:63] offset:30720
	ds_write_b128 v131, v[64:67] offset:36864
	ds_write_b128 v131, v[68:71] offset:43008
	s_cmp_eq_u32 s84, 1
	s_cbranch_scc1 .Lg2l_z_10
	ds_write_b128 v131, v[72:75] offset:49152
.Lg2l_z_10:
	ds_write_b128 v131, v[76:79] offset:55296
	s_and_saveexec_b64 s[8:9], s[6:7]
	s_cbranch_execz .Lg2l_nocd_11
	s_lshl_b32 s0, s0, 2
	v_add_u32_e32 v130, s0, v132
	ds_write_b32 v130, v128

.Lg2l_tail_9:
	s_and_b32 s0, s81, 1
	v_lshl_add_u32 v131, s0, 16, v125
	s_waitcnt vmcnt(0)
	ds_write_b128 v131, v[40:43]
	ds_write_b128 v131, v[44:47] offset:6144
	ds_write_b128 v131, v[48:51] offset:12288
	ds_write_b128 v131, v[52:55] offset:18432
	ds_write_b128 v131, v[56:59] offset:24576
	ds_write_b128 v131, v[60:63] offset:30720
	ds_write_b128 v131, v[64:67] offset:36864
	ds_write_b128 v131, v[68:71] offset:43008
	s_cmp_eq_u32 s84, 1
	s_cbranch_scc1 .Lg2l_z_12
	ds_write_b128 v131, v[72:75] offset:49152

.Lg2l_nold_9:
	s_waitcnt lgkmcnt(0)
	s_barrier
	s_add_i32 s81, s81, 1
	s_cmpk_lt_u32 s81, 0x100
	s_cbranch_scc0 .Lg2l_exit
	s_cmpk_lt_u32 s81, 0xf0
	s_cbranch_scc0 .Lg2l_tail_15
	s_and_b32 s0, s81, 1
	v_lshl_add_u32 v131, s0, 16, v125
	s_waitcnt vmcnt(22)
	ds_write_b128 v131, v[80:83]
	ds_write_b128 v131, v[84:87] offset:6144
	ds_write_b128 v131, v[88:91] offset:12288
	ds_write_b128 v131, v[92:95] offset:18432
	ds_write_b128 v131, v[96:99] offset:24576
	ds_write_b128 v131, v[100:103] offset:30720
	ds_write_b128 v131, v[104:107] offset:36864
	ds_write_b128 v131, v[108:111] offset:43008
	s_cmp_eq_u32 s84, 1
	s_cbranch_scc1 .Lg2l_z_16
	ds_write_b128 v131, v[112:115] offset:49152
.Lg2l_z_16:
	ds_write_b128 v131, v[116:119] offset:55296
	s_and_saveexec_b64 s[8:9], s[6:7]
	s_cbranch_execz .Lg2l_nocd_17
	s_lshl_b32 s0, s0, 2
	v_add_u32_e32 v130, s0, v132
	ds_write_b32 v130, v129

.Lg2l_tail_15:
	s_and_b32 s0, s81, 1
	v_lshl_add_u32 v131, s0, 16, v125
	s_waitcnt vmcnt(0)
	ds_write_b128 v131, v[80:83]
	ds_write_b128 v131, v[84:87] offset:6144
	ds_write_b128 v131, v[88:91] offset:12288
	ds_write_b128 v131, v[92:95] offset:18432
	ds_write_b128 v131, v[96:99] offset:24576
	ds_write_b128 v131, v[100:103] offset:30720
	ds_write_b128 v131, v[104:107] offset:36864
	ds_write_b128 v131, v[108:111] offset:43008
	s_cmp_eq_u32 s84, 1
	s_cbranch_scc1 .Lg2l_z_18
	ds_write_b128 v131, v[112:115] offset:49152
